# transpose loops: idx remapped so a wave writes whole destination lines (8 columns x 64 keys) instead of 8/16-byte pieces; prep0 head-norm loop unrolled x4 with hoisted gains
# speedup vs baseline: 1.0491x; 1.0230x over previous
.LBB0_488:
	v_lshrrev_b32_e32 v120, 9, v1
	v_bfe_u32 v121, v1, 3, 3
	v_lshrrev_b32_e32 v122, 4, v120
	v_lshl_or_b32 v122, v122, 3, v121
	v_and_b32_e32 v120, 15, v120
	v_bfe_u32 v121, v1, 6, 3
	v_lshl_or_b32 v120, v120, 3, v121
	v_and_b32_e32 v121, 7, v1
	v_lshl_or_b32 v120, v120, 3, v121
	v_mov_b32_e32 v12, v122
	v_lshlrev_b32_e32 v9, 10, v122
	v_lshlrev_b32_e32 v2, 10, v122
	v_mov_b32_e32 v13, v120
	v_lshlrev_b32_e32 v2, 1, v2
	v_lshlrev_b32_e32 v2, 1, v13
	v_and_b32_e32 v6, 0xffffff80, v2
	v_lshlrev_b32_e32 v4, 3, v12
	v_ashrrev_i32_e32 v7, 31, v6
	v_and_b32_e32 v2, 63, v13
	v_lshl_add_u64 v[6:7], v[6:7], 1, s[8:9]
	v_lshlrev_b32_e32 v2, 1, v2
	v_ashrrev_i32_e32 v5, 31, v4
	v_lshl_add_u64 v[6:7], v[6:7], 0, v[2:3]
	v_lshlrev_b64 v[10:11], 12, v[4:5]
	v_lshl_add_u64 v[10:11], v[6:7], 0, v[10:11]
	global_load_ushort v14, v[10:11], off offset:128
	v_or_b32_e32 v10, 1, v4
	v_ashrrev_i32_e32 v11, 31, v10
	v_lshlrev_b64 v[10:11], 12, v[10:11]
	v_lshl_add_u64 v[10:11], v[6:7], 0, v[10:11]
	global_load_ushort v15, v[10:11], off offset:128
	v_or_b32_e32 v10, 2, v4
	v_ashrrev_i32_e32 v11, 31, v10
	v_lshlrev_b64 v[10:11], 12, v[10:11]
	v_lshl_add_u64 v[10:11], v[6:7], 0, v[10:11]
	global_load_ushort v16, v[10:11], off offset:128
	v_or_b32_e32 v10, 3, v4
	v_ashrrev_i32_e32 v11, 31, v10
	v_lshlrev_b64 v[10:11], 12, v[10:11]
	v_lshl_add_u64 v[10:11], v[6:7], 0, v[10:11]
	global_load_ushort v17, v[10:11], off offset:128
	v_or_b32_e32 v10, 4, v4
	v_ashrrev_i32_e32 v11, 31, v10
	v_lshlrev_b64 v[10:11], 12, v[10:11]
	v_lshl_add_u64 v[10:11], v[6:7], 0, v[10:11]
	global_load_ushort v18, v[10:11], off offset:128
	v_or_b32_e32 v10, 5, v4
	v_ashrrev_i32_e32 v11, 31, v10
	v_lshlrev_b64 v[10:11], 12, v[10:11]
	v_lshl_add_u64 v[10:11], v[6:7], 0, v[10:11]
	global_load_ushort v19, v[10:11], off offset:128
	v_or_b32_e32 v10, 6, v4
	v_ashrrev_i32_e32 v11, 31, v10
	v_lshlrev_b64 v[10:11], 12, v[10:11]
	v_lshl_add_u64 v[10:11], v[6:7], 0, v[10:11]
	global_load_ushort v20, v[10:11], off offset:128
	v_or_b32_e32 v10, 7, v4
	v_ashrrev_i32_e32 v11, 31, v10
	v_lshlrev_b64 v[10:11], 12, v[10:11]
	v_lshl_add_u64 v[6:7], v[6:7], 0, v[10:11]
	global_load_ushort v21, v[6:7], off offset:128
	v_ashrrev_i16_e32 v2, 15, v13
	v_lshrrev_b16_e32 v2, 10, v2
	v_add_u16_e32 v2, v13, v2
	v_ashrrev_i16_e32 v5, 6, v2
	v_bfe_i32 v6, v5, 0, 16
	v_ashrrev_i32_e32 v7, 31, v6
	v_ashrrev_i32_e32 v10, 12, v9
	v_lshlrev_b64 v[6:7], 19, v[6:7]
	v_ashrrev_i32_e32 v11, 31, v10
	v_and_b32_e32 v2, 0xffffffc0, v2
	v_lshl_add_u64 v[6:7], s[56:57], 0, v[6:7]
	v_lshlrev_b64 v[10:11], 12, v[10:11]
	v_sub_u16_e32 v2, v13, v2
	v_lshl_add_u64 v[6:7], v[6:7], 0, v[10:11]
	v_lshlrev_b32_sdwa v10, v229, sext(v2) dst_sel:DWORD dst_unused:UNUSED_PAD src0_sel:DWORD src1_sel:WORD_0
	v_ashrrev_i32_e32 v11, 31, v10
	v_lshlrev_b32_e32 v2, 4, v12
	v_lshl_add_u64 v[6:7], v[10:11], 1, v[6:7]
	v_and_b32_e32 v2, 32, v2
	v_lshl_add_u64 v[6:7], v[6:7], 0, v[2:3]
	v_and_b32_e32 v2, 8, v4
	v_add_u32_e32 v1, s2, v1
	v_lshl_add_u64 v[4:5], v[6:7], 0, v[2:3]
	v_cmp_lt_i32_e32 vcc, s6, v1
	v_add_u32_e32 v8, s3, v8
	s_or_b64 s[4:5], vcc, s[4:5]
	s_waitcnt vmcnt(0)
	v_perm_b32 v6, v15, v14, s23
	v_perm_b32 v7, v17, v16, s23
	global_store_dwordx2 v[4:5], v[6:7], off
	v_perm_b32 v6, v19, v18, s23
	v_perm_b32 v7, v21, v20, s23
	global_store_dwordx2 v[4:5], v[6:7], off offset:16
	s_andn2_b64 exec, exec, s[4:5]
	s_cbranch_execnz .LBB0_488

.LBB0_493:
	v_lshrrev_b32_e32 v120, 9, v1
	v_bfe_u32 v121, v1, 3, 3
	v_lshrrev_b32_e32 v122, 4, v120
	v_lshl_or_b32 v122, v122, 3, v121
	v_and_b32_e32 v120, 15, v120
	v_bfe_u32 v121, v1, 6, 3
	v_lshl_or_b32 v120, v120, 3, v121
	v_and_b32_e32 v121, 7, v1
	v_lshl_or_b32 v120, v120, 3, v121
	v_mov_b32_e32 v7, v122
	v_lshlrev_b32_e32 v2, 10, v122
	v_mov_b32_e32 v12, v120
	v_lshlrev_b32_e32 v2, 1, v2
	v_lshlrev_b32_e32 v2, 1, v12
	v_lshlrev_b32_e32 v13, 3, v7
	v_and_b32_e32 v4, 0xffffff80, v2
	v_add_u32_e32 v8, s16, v13
	v_ashrrev_i32_e32 v5, 31, v4
	v_and_b32_e32 v2, 63, v12
	v_lshl_add_u64 v[4:5], v[4:5], 1, s[8:9]
	v_lshlrev_b32_e32 v2, 1, v2
	v_ashrrev_i32_e32 v9, 31, v8
	v_lshl_add_u64 v[4:5], v[4:5], 0, v[2:3]
	v_lshlrev_b64 v[10:11], 12, v[8:9]
	v_lshl_add_u64 v[10:11], v[4:5], 0, v[10:11]
	global_load_ushort v14, v[10:11], off offset:128
	v_or_b32_e32 v10, 1, v8
	v_ashrrev_i32_e32 v11, 31, v10
	v_lshlrev_b64 v[10:11], 12, v[10:11]
	v_lshl_add_u64 v[10:11], v[4:5], 0, v[10:11]
	global_load_ushort v15, v[10:11], off offset:128
	v_or_b32_e32 v10, 2, v8
	v_ashrrev_i32_e32 v11, 31, v10
	v_lshlrev_b64 v[10:11], 12, v[10:11]
	v_lshl_add_u64 v[10:11], v[4:5], 0, v[10:11]
	global_load_ushort v16, v[10:11], off offset:128
	v_or_b32_e32 v10, 3, v8
	v_ashrrev_i32_e32 v11, 31, v10
	v_lshlrev_b64 v[10:11], 12, v[10:11]
	v_lshl_add_u64 v[10:11], v[4:5], 0, v[10:11]
	global_load_ushort v17, v[10:11], off offset:128
	v_or_b32_e32 v10, 4, v8
	v_ashrrev_i32_e32 v11, 31, v10
	v_lshlrev_b64 v[10:11], 12, v[10:11]
	v_lshl_add_u64 v[10:11], v[4:5], 0, v[10:11]
	global_load_ushort v18, v[10:11], off offset:128
	v_or_b32_e32 v10, 5, v8
	v_ashrrev_i32_e32 v11, 31, v10
	v_lshlrev_b64 v[10:11], 12, v[10:11]
	v_lshl_add_u64 v[10:11], v[4:5], 0, v[10:11]
	global_load_ushort v19, v[10:11], off offset:128
	v_or_b32_e32 v10, 6, v8
	v_or_b32_e32 v8, 7, v8
	v_ashrrev_i32_e32 v11, 31, v10
	v_ashrrev_i32_e32 v9, 31, v8
	v_lshlrev_b64 v[10:11], 12, v[10:11]
	v_lshlrev_b64 v[8:9], 12, v[8:9]
	v_lshl_add_u64 v[10:11], v[4:5], 0, v[10:11]
	v_lshl_add_u64 v[4:5], v[4:5], 0, v[8:9]
	global_load_ushort v10, v[10:11], off offset:128
	v_add_u32_e32 v2, 0x100, v13
	global_load_ushort v11, v[4:5], off offset:128
	v_ashrrev_i16_e32 v4, 15, v12
	v_lshrrev_b16_e32 v4, 10, v4
	v_add_u16_e32 v20, v12, v4
	v_ashrrev_i16_e32 v4, 6, v20
	v_ashrrev_i32_e32 v8, 5, v2
	v_mul_hi_i32_i24_sdwa v5, sext(v4), s59 dst_sel:DWORD dst_unused:UNUSED_PAD src0_sel:WORD_0 src1_sel:DWORD
	v_mul_i32_i24_sdwa v4, sext(v4), s59 dst_sel:DWORD dst_unused:UNUSED_PAD src0_sel:WORD_0 src1_sel:DWORD
	v_ashrrev_i32_e32 v9, 31, v8
	v_and_b32_e32 v2, 0xffffffc0, v20
	v_lshl_add_u64 v[4:5], s[0:1], 0, v[4:5]
	v_lshlrev_b64 v[8:9], 12, v[8:9]
	v_sub_u16_e32 v2, v12, v2
	v_lshl_add_u64 v[4:5], v[4:5], 0, v[8:9]
	v_lshlrev_b32_sdwa v8, v229, sext(v2) dst_sel:DWORD dst_unused:UNUSED_PAD src0_sel:DWORD src1_sel:WORD_0
	v_ashrrev_i32_e32 v9, 31, v8
	v_lshlrev_b32_e32 v2, 4, v7
	v_lshl_add_u64 v[4:5], v[8:9], 1, v[4:5]
	v_and_b32_e32 v2, 32, v2
	v_lshl_add_u64 v[4:5], v[4:5], 0, v[2:3]
	v_and_b32_e32 v2, 8, v13
	v_add_u32_e32 v1, s3, v1
	v_lshl_add_u64 v[4:5], v[4:5], 0, v[2:3]
	v_cmp_lt_i32_e32 vcc, s19, v1
	v_add_u32_e32 v6, s17, v6
	s_or_b64 s[14:15], vcc, s[14:15]
	s_waitcnt vmcnt(0)
	v_perm_b32 v8, v15, v14, s23
	v_perm_b32 v9, v17, v16, s23
	global_store_dwordx2 v[4:5], v[8:9], off
	v_perm_b32 v8, v19, v18, s23
	v_perm_b32 v9, v11, v10, s23
	global_store_dwordx2 v[4:5], v[8:9], off offset:16
	s_andn2_b64 exec, exec, s[14:15]
	s_cbranch_execnz .LBB0_493

.LBB0_496:
	v_lshrrev_b32_e32 v120, 9, v1
	v_bfe_u32 v121, v1, 3, 3
	v_lshrrev_b32_e32 v122, 4, v120
	v_lshl_or_b32 v122, v122, 3, v121
	v_and_b32_e32 v120, 15, v120
	v_bfe_u32 v121, v1, 6, 3
	v_lshl_or_b32 v120, v120, 3, v121
	v_and_b32_e32 v121, 7, v1
	v_lshl_or_b32 v120, v120, 3, v121
	v_mov_b32_e32 v12, v122
	v_lshlrev_b32_e32 v7, 10, v122
	v_lshlrev_b32_e32 v2, 10, v122
	v_mov_b32_e32 v13, v120
	v_lshlrev_b32_e32 v2, 1, v2
	v_lshlrev_b32_e32 v2, 1, v13
	v_lshlrev_b32_e32 v14, 3, v12
	v_and_b32_e32 v4, 0xffffff80, v2
	v_add_u32_e32 v8, s3, v14
	v_ashrrev_i32_e32 v5, 31, v4
	v_and_b32_e32 v2, 63, v13
	v_lshl_add_u64 v[4:5], v[4:5], 1, s[8:9]
	v_lshlrev_b32_e32 v2, 1, v2
	v_ashrrev_i32_e32 v9, 31, v8
	v_lshl_add_u64 v[4:5], v[4:5], 0, v[2:3]
	v_lshlrev_b64 v[10:11], 12, v[8:9]
	v_lshl_add_u64 v[10:11], v[4:5], 0, v[10:11]
	global_load_ushort v15, v[10:11], off offset:128
	v_or_b32_e32 v10, 1, v8
	v_ashrrev_i32_e32 v11, 31, v10
	v_lshlrev_b64 v[10:11], 12, v[10:11]
	v_lshl_add_u64 v[10:11], v[4:5], 0, v[10:11]
	global_load_ushort v16, v[10:11], off offset:128
	v_or_b32_e32 v10, 2, v8
	v_ashrrev_i32_e32 v11, 31, v10
	v_lshlrev_b64 v[10:11], 12, v[10:11]
	v_lshl_add_u64 v[10:11], v[4:5], 0, v[10:11]
	global_load_ushort v17, v[10:11], off offset:128
	v_or_b32_e32 v10, 3, v8
	v_ashrrev_i32_e32 v11, 31, v10
	v_lshlrev_b64 v[10:11], 12, v[10:11]
	v_lshl_add_u64 v[10:11], v[4:5], 0, v[10:11]
	global_load_ushort v18, v[10:11], off offset:128
	v_or_b32_e32 v10, 4, v8
	v_ashrrev_i32_e32 v11, 31, v10
	v_lshlrev_b64 v[10:11], 12, v[10:11]
	v_lshl_add_u64 v[10:11], v[4:5], 0, v[10:11]
	global_load_ushort v19, v[10:11], off offset:128
	v_or_b32_e32 v10, 5, v8
	v_ashrrev_i32_e32 v11, 31, v10
	v_lshlrev_b64 v[10:11], 12, v[10:11]
	v_lshl_add_u64 v[10:11], v[4:5], 0, v[10:11]
	global_load_ushort v20, v[10:11], off offset:128
	v_or_b32_e32 v10, 6, v8
	v_or_b32_e32 v8, 7, v8
	v_ashrrev_i32_e32 v11, 31, v10
	v_ashrrev_i32_e32 v9, 31, v8
	v_lshlrev_b64 v[10:11], 12, v[10:11]
	v_lshlrev_b64 v[8:9], 12, v[8:9]
	v_lshl_add_u64 v[10:11], v[4:5], 0, v[10:11]
	v_lshl_add_u64 v[4:5], v[4:5], 0, v[8:9]
	global_load_ushort v10, v[10:11], off offset:128
	v_ashrrev_i16_e32 v2, 15, v13
	global_load_ushort v11, v[4:5], off offset:128
	v_lshrrev_b16_e32 v2, 10, v2
	v_add_u16_e32 v2, v13, v2
	v_ashrrev_i16_e32 v4, 6, v2
	v_ashrrev_i32_e32 v8, 12, v7
	v_mul_hi_i32_i24_sdwa v5, sext(v4), s59 dst_sel:DWORD dst_unused:UNUSED_PAD src0_sel:WORD_0 src1_sel:DWORD
	v_mul_i32_i24_sdwa v4, sext(v4), s59 dst_sel:DWORD dst_unused:UNUSED_PAD src0_sel:WORD_0 src1_sel:DWORD
	v_ashrrev_i32_e32 v9, 31, v8
	v_and_b32_e32 v2, 0xffffffc0, v2
	v_lshl_add_u64 v[4:5], s[0:1], 0, v[4:5]
	v_lshlrev_b64 v[8:9], 12, v[8:9]
	v_sub_u16_e32 v2, v13, v2
	v_lshl_add_u64 v[4:5], v[4:5], 0, v[8:9]
	v_lshlrev_b32_sdwa v8, v229, sext(v2) dst_sel:DWORD dst_unused:UNUSED_PAD src0_sel:DWORD src1_sel:WORD_0
	v_ashrrev_i32_e32 v9, 31, v8
	v_lshlrev_b32_e32 v2, 4, v12
	v_lshl_add_u64 v[4:5], v[8:9], 1, v[4:5]
	v_and_b32_e32 v2, 32, v2
	v_lshl_add_u64 v[4:5], v[4:5], 0, v[2:3]
	v_and_b32_e32 v2, 8, v14
	v_add_u32_e32 v1, s2, v1
	v_lshl_add_u64 v[4:5], v[4:5], 0, v[2:3]
	v_cmp_lt_i32_e32 vcc, s73, v1
	v_add_u32_e32 v6, s16, v6
	s_or_b64 s[14:15], vcc, s[14:15]
	s_waitcnt vmcnt(0)
	v_perm_b32 v8, v16, v15, s23
	v_perm_b32 v9, v18, v17, s23
	global_store_dwordx2 v[4:5], v[8:9], off
	v_perm_b32 v8, v20, v19, s23
	v_perm_b32 v9, v11, v10, s23
	global_store_dwordx2 v[4:5], v[8:9], off offset:16
	s_andn2_b64 exec, exec, s[14:15]
	s_cbranch_execnz .LBB0_496
	s_branch .LBB0_490

.LBB0_741:
	v_lshrrev_b32_e32 v120, 9, v1
	v_bfe_u32 v121, v1, 3, 3
	v_lshrrev_b32_e32 v122, 4, v120
	v_lshl_or_b32 v122, v122, 3, v121
	v_and_b32_e32 v120, 15, v120
	v_bfe_u32 v121, v1, 6, 3
	v_lshl_or_b32 v120, v120, 3, v121
	v_and_b32_e32 v121, 7, v1
	v_lshl_or_b32 v120, v120, 3, v121
	v_mov_b32_e32 v2, v122
	v_lshlrev_b32_e32 v11, 10, v122
	v_mov_b32_e32 v4, v120
	v_lshlrev_b32_e32 v10, 3, v2
	v_ashrrev_i32_e32 v5, 31, v4
	v_mov_b64_e32 v[8:9], s[34:35]
	v_mad_i64_i32 v[12:13], s[10:11], v10, s67, v[8:9]
	v_lshlrev_b64 v[6:7], 1, v[4:5]
	v_lshl_add_u64 v[12:13], v[12:13], 0, v[6:7]
	v_add_co_u32_e32 v12, vcc, 0x1000, v12
	v_or_b32_e32 v5, 1, v10
	s_nop 0
	v_addc_co_u32_e32 v13, vcc, 0, v13, vcc
	global_load_ushort v14, v[12:13], off
	v_mad_i64_i32 v[12:13], s[10:11], v5, s67, v[8:9]
	v_lshl_add_u64 v[12:13], v[12:13], 0, v[6:7]
	v_add_co_u32_e32 v12, vcc, 0x1000, v12
	v_or_b32_e32 v5, 2, v10
	s_nop 0
	v_addc_co_u32_e32 v13, vcc, 0, v13, vcc
	global_load_ushort v15, v[12:13], off
	v_mad_i64_i32 v[12:13], s[10:11], v5, s67, v[8:9]
	v_lshl_add_u64 v[12:13], v[12:13], 0, v[6:7]
	v_add_co_u32_e32 v12, vcc, 0x1000, v12
	v_or_b32_e32 v5, 3, v10
	s_nop 0
	v_addc_co_u32_e32 v13, vcc, 0, v13, vcc
	global_load_ushort v16, v[12:13], off
	v_mad_i64_i32 v[12:13], s[10:11], v5, s67, v[8:9]
	v_lshl_add_u64 v[12:13], v[12:13], 0, v[6:7]
	v_add_co_u32_e32 v12, vcc, 0x1000, v12
	v_or_b32_e32 v5, 4, v10
	s_nop 0
	v_addc_co_u32_e32 v13, vcc, 0, v13, vcc
	global_load_ushort v17, v[12:13], off
	v_mad_i64_i32 v[12:13], s[10:11], v5, s67, v[8:9]
	v_lshl_add_u64 v[12:13], v[12:13], 0, v[6:7]
	v_add_co_u32_e32 v12, vcc, 0x1000, v12
	v_or_b32_e32 v5, 5, v10
	s_nop 0
	v_addc_co_u32_e32 v13, vcc, 0, v13, vcc
	global_load_ushort v18, v[12:13], off
	v_mad_i64_i32 v[12:13], s[10:11], v5, s67, v[8:9]
	v_lshl_add_u64 v[12:13], v[12:13], 0, v[6:7]
	v_add_co_u32_e32 v12, vcc, 0x1000, v12
	v_or_b32_e32 v5, 6, v10
	s_nop 0
	v_addc_co_u32_e32 v13, vcc, 0, v13, vcc
	global_load_ushort v19, v[12:13], off
	v_mad_i64_i32 v[12:13], s[10:11], v5, s67, v[8:9]
	v_lshl_add_u64 v[12:13], v[12:13], 0, v[6:7]
	v_or_b32_e32 v5, 7, v10
	v_add_co_u32_e32 v12, vcc, 0x1000, v12
	v_mad_i64_i32 v[8:9], s[10:11], v5, s67, v[8:9]
	s_nop 0
	v_addc_co_u32_e32 v13, vcc, 0, v13, vcc
	v_lshl_add_u64 v[6:7], v[8:9], 0, v[6:7]
	v_add_co_u32_e32 v6, vcc, 0x1000, v6
	global_load_ushort v12, v[12:13], off
	s_nop 0
	v_addc_co_u32_e32 v7, vcc, 0, v7, vcc
	global_load_ushort v13, v[6:7], off
	v_ashrrev_i16_e32 v5, 15, v4
	v_lshrrev_b16_e32 v5, 9, v5
	v_add_u16_e32 v5, v4, v5
	v_ashrrev_i16_e32 v6, 7, v5
	v_bfe_i32 v6, v6, 0, 16
	v_ashrrev_i32_e32 v7, 31, v6
	v_ashrrev_i32_e32 v8, 12, v11
	v_and_b32_e32 v5, 0xffffff80, v5
	v_lshlrev_b64 v[6:7], 20, v[6:7]
	v_ashrrev_i32_e32 v9, 31, v8
	v_sub_u16_e32 v4, v4, v5
	v_lshl_add_u64 v[6:7], s[4:5], 0, v[6:7]
	v_lshlrev_b64 v[8:9], 13, v[8:9]
	v_lshlrev_b32_sdwa v4, v229, sext(v4) dst_sel:DWORD dst_unused:UNUSED_PAD src0_sel:DWORD src1_sel:WORD_0
	v_lshl_add_u64 v[6:7], v[6:7], 0, v[8:9]
	v_ashrrev_i32_e32 v5, 31, v4
	v_lshlrev_b32_e32 v2, 4, v2
	v_lshl_add_u64 v[4:5], v[4:5], 1, v[6:7]
	v_and_b32_e32 v2, 32, v2
	v_lshl_add_u64 v[4:5], v[4:5], 0, v[2:3]
	v_and_b32_e32 v2, 8, v10
	v_add_u32_e32 v1, s2, v1
	v_lshl_add_u64 v[4:5], v[4:5], 0, v[2:3]
	v_cmp_lt_i32_e32 vcc, s42, v1
	s_or_b64 s[6:7], vcc, s[6:7]
	s_waitcnt vmcnt(0)
	v_perm_b32 v6, v15, v14, s23
	v_perm_b32 v7, v17, v16, s23
	global_store_dwordx2 v[4:5], v[6:7], off
	v_perm_b32 v6, v19, v18, s23
	v_perm_b32 v7, v13, v12, s23
	global_store_dwordx2 v[4:5], v[6:7], off offset:16
	s_andn2_b64 exec, exec, s[6:7]
	s_cbranch_execnz .LBB0_741

.LBB0_744:
	v_lshrrev_b32_e32 v120, 9, v1
	v_bfe_u32 v121, v1, 3, 3
	v_lshrrev_b32_e32 v122, 4, v120
	v_lshl_or_b32 v122, v122, 3, v121
	v_and_b32_e32 v120, 15, v120
	v_bfe_u32 v121, v1, 6, 3
	v_lshl_or_b32 v120, v120, 3, v121
	v_and_b32_e32 v121, 7, v1
	v_lshl_or_b32 v120, v120, 3, v121
	v_mov_b32_e32 v2, v122
	v_mov_b32_e32 v4, v120
	v_lshlrev_b32_e32 v10, 3, v2
	v_add_u32_e32 v6, 0x1000, v10
	v_ashrrev_i32_e32 v5, 31, v4
	v_mov_b64_e32 v[8:9], s[34:35]
	v_mad_i64_i32 v[12:13], s[10:11], v6, s67, v[8:9]
	v_lshlrev_b64 v[6:7], 1, v[4:5]
	v_lshl_add_u64 v[12:13], v[12:13], 0, v[6:7]
	v_add_co_u32_e32 v12, vcc, s12, v12
	v_add_u32_e32 v11, 0x1001, v10
	s_nop 0
	v_addc_co_u32_e32 v13, vcc, 0, v13, vcc
	global_load_ushort v5, v[12:13], off
	v_mad_i64_i32 v[12:13], s[10:11], v11, s67, v[8:9]
	v_lshl_add_u64 v[12:13], v[12:13], 0, v[6:7]
	v_add_co_u32_e32 v12, vcc, s12, v12
	v_lshlrev_b32_e32 v2, 4, v2
	s_nop 0
	v_addc_co_u32_e32 v13, vcc, 0, v13, vcc
	global_load_ushort v11, v[12:13], off
	v_add_u32_e32 v12, 0x1002, v10
	v_mad_i64_i32 v[12:13], s[10:11], v12, s67, v[8:9]
	v_lshl_add_u64 v[12:13], v[12:13], 0, v[6:7]
	v_add_co_u32_e32 v12, vcc, s12, v12
	v_and_b32_e32 v2, 32, v2
	s_nop 0
	v_addc_co_u32_e32 v13, vcc, 0, v13, vcc
	global_load_ushort v14, v[12:13], off
	v_add_u32_e32 v12, 0x1003, v10
	v_mad_i64_i32 v[12:13], s[10:11], v12, s67, v[8:9]
	v_lshl_add_u64 v[12:13], v[12:13], 0, v[6:7]
	v_add_co_u32_e32 v12, vcc, s12, v12
	v_add_u32_e32 v1, s2, v1
	s_nop 0
	v_addc_co_u32_e32 v13, vcc, 0, v13, vcc
	global_load_ushort v15, v[12:13], off
	v_add_u32_e32 v12, 0x1004, v10
	v_mad_i64_i32 v[12:13], s[10:11], v12, s67, v[8:9]
	v_lshl_add_u64 v[12:13], v[12:13], 0, v[6:7]
	v_add_co_u32_e32 v12, vcc, s12, v12
	s_nop 1
	v_addc_co_u32_e32 v13, vcc, 0, v13, vcc
	global_load_ushort v16, v[12:13], off
	v_add_u32_e32 v12, 0x1005, v10
	v_mad_i64_i32 v[12:13], s[10:11], v12, s67, v[8:9]
	v_lshl_add_u64 v[12:13], v[12:13], 0, v[6:7]
	v_add_co_u32_e32 v12, vcc, s12, v12
	s_nop 1
	v_addc_co_u32_e32 v13, vcc, 0, v13, vcc
	global_load_ushort v17, v[12:13], off
	v_add_u32_e32 v12, 0x1006, v10
	v_mad_i64_i32 v[12:13], s[10:11], v12, s67, v[8:9]
	v_lshl_add_u64 v[12:13], v[12:13], 0, v[6:7]
	v_add_co_u32_e32 v12, vcc, s12, v12
	s_nop 1
	v_addc_co_u32_e32 v13, vcc, 0, v13, vcc
	global_load_ushort v12, v[12:13], off
	v_add_u32_e32 v13, 0x1007, v10
	v_mad_i64_i32 v[8:9], s[10:11], v13, s67, v[8:9]
	v_lshl_add_u64 v[6:7], v[8:9], 0, v[6:7]
	v_add_co_u32_e32 v6, vcc, s12, v6
	v_add_u32_e32 v8, 0x100, v10
	s_nop 0
	v_addc_co_u32_e32 v7, vcc, 0, v7, vcc
	global_load_ushort v13, v[6:7], off
	v_ashrrev_i16_e32 v6, 15, v4
	v_lshrrev_b16_e32 v6, 9, v6
	v_add_u16_e32 v18, v4, v6
	v_ashrrev_i16_e32 v6, 7, v18
	v_ashrrev_i32_e32 v8, 5, v8
	v_mul_hi_i32_i24_sdwa v7, sext(v6), s13 dst_sel:DWORD dst_unused:UNUSED_PAD src0_sel:WORD_0 src1_sel:DWORD
	v_mul_i32_i24_sdwa v6, sext(v6), s13 dst_sel:DWORD dst_unused:UNUSED_PAD src0_sel:WORD_0 src1_sel:DWORD
	v_ashrrev_i32_e32 v9, 31, v8
	v_lshl_add_u64 v[6:7], s[0:1], 0, v[6:7]
	v_lshlrev_b64 v[8:9], 13, v[8:9]
	v_lshl_add_u64 v[6:7], v[6:7], 0, v[8:9]
	v_and_b32_e32 v8, 0xffffff80, v18
	v_sub_u16_e32 v4, v4, v8
	v_lshlrev_b32_sdwa v8, v229, sext(v4) dst_sel:DWORD dst_unused:UNUSED_PAD src0_sel:DWORD src1_sel:WORD_0
	v_ashrrev_i32_e32 v9, 31, v8
	v_lshl_add_u64 v[6:7], v[8:9], 1, v[6:7]
	v_lshl_add_u64 v[6:7], v[6:7], 0, v[2:3]
	v_and_b32_e32 v2, 8, v10
	v_cmp_lt_i32_e32 vcc, s41, v1
	v_lshl_add_u64 v[6:7], v[6:7], 0, v[2:3]
	s_waitcnt vmcnt(0)
	v_perm_b32 v8, v11, v5, s23
	s_or_b64 s[6:7], vcc, s[6:7]
	v_perm_b32 v9, v15, v14, s23
	global_store_dwordx2 v[6:7], v[8:9], off
	v_perm_b32 v4, v17, v16, s23
	v_perm_b32 v5, v13, v12, s23
	global_store_dwordx2 v[6:7], v[4:5], off offset:16
	s_andn2_b64 exec, exec, s[6:7]
	s_cbranch_execnz .LBB0_744

.LBB0_747:
	v_lshrrev_b32_e32 v120, 9, v1
	v_bfe_u32 v121, v1, 3, 3
	v_lshrrev_b32_e32 v122, 4, v120
	v_lshl_or_b32 v122, v122, 3, v121
	v_and_b32_e32 v120, 15, v120
	v_bfe_u32 v121, v1, 6, 3
	v_lshl_or_b32 v120, v120, 3, v121
	v_and_b32_e32 v121, 7, v1
	v_lshl_or_b32 v120, v120, 3, v121
	v_mov_b32_e32 v2, v122
	v_mov_b32_e32 v4, v120
	v_lshlrev_b32_e32 v10, 3, v2
	v_add_u32_e32 v6, 0x1800, v10
	v_ashrrev_i32_e32 v5, 31, v4
	v_mov_b64_e32 v[8:9], s[34:35]
	v_mad_i64_i32 v[12:13], s[12:13], v6, s67, v[8:9]
	v_lshlrev_b64 v[6:7], 1, v[4:5]
	v_lshl_add_u64 v[12:13], v[12:13], 0, v[6:7]
	v_add_co_u32_e32 v12, vcc, s14, v12
	v_add_u32_e32 v11, 0x1801, v10
	s_nop 0
	v_addc_co_u32_e32 v13, vcc, 0, v13, vcc
	global_load_ushort v5, v[12:13], off
	v_mad_i64_i32 v[12:13], s[12:13], v11, s67, v[8:9]
	v_lshl_add_u64 v[12:13], v[12:13], 0, v[6:7]
	v_add_co_u32_e32 v12, vcc, s14, v12
	v_lshlrev_b32_e32 v2, 4, v2
	s_nop 0
	v_addc_co_u32_e32 v13, vcc, 0, v13, vcc
	global_load_ushort v11, v[12:13], off
	v_add_u32_e32 v12, 0x1802, v10
	v_mad_i64_i32 v[12:13], s[12:13], v12, s67, v[8:9]
	v_lshl_add_u64 v[12:13], v[12:13], 0, v[6:7]
	v_add_co_u32_e32 v12, vcc, s14, v12
	v_and_b32_e32 v2, 32, v2
	s_nop 0
	v_addc_co_u32_e32 v13, vcc, 0, v13, vcc
	global_load_ushort v14, v[12:13], off
	v_add_u32_e32 v12, 0x1803, v10
	v_mad_i64_i32 v[12:13], s[12:13], v12, s67, v[8:9]
	v_lshl_add_u64 v[12:13], v[12:13], 0, v[6:7]
	v_add_co_u32_e32 v12, vcc, s14, v12
	v_add_u32_e32 v1, s2, v1
	s_nop 0
	v_addc_co_u32_e32 v13, vcc, 0, v13, vcc
	global_load_ushort v15, v[12:13], off
	v_add_u32_e32 v12, 0x1804, v10
	v_mad_i64_i32 v[12:13], s[12:13], v12, s67, v[8:9]
	v_lshl_add_u64 v[12:13], v[12:13], 0, v[6:7]
	v_add_co_u32_e32 v12, vcc, s14, v12
	s_nop 1
	v_addc_co_u32_e32 v13, vcc, 0, v13, vcc
	global_load_ushort v16, v[12:13], off
	v_add_u32_e32 v12, 0x1805, v10
	v_mad_i64_i32 v[12:13], s[12:13], v12, s67, v[8:9]
	v_lshl_add_u64 v[12:13], v[12:13], 0, v[6:7]
	v_add_co_u32_e32 v12, vcc, s14, v12
	s_nop 1
	v_addc_co_u32_e32 v13, vcc, 0, v13, vcc
	global_load_ushort v17, v[12:13], off
	v_add_u32_e32 v12, 0x1806, v10
	v_mad_i64_i32 v[12:13], s[12:13], v12, s67, v[8:9]
	v_lshl_add_u64 v[12:13], v[12:13], 0, v[6:7]
	v_add_co_u32_e32 v12, vcc, s14, v12
	s_nop 1
	v_addc_co_u32_e32 v13, vcc, 0, v13, vcc
	global_load_ushort v12, v[12:13], off
	v_add_u32_e32 v13, 0x1807, v10
	v_mad_i64_i32 v[8:9], s[12:13], v13, s67, v[8:9]
	v_lshl_add_u64 v[6:7], v[8:9], 0, v[6:7]
	v_add_co_u32_e32 v6, vcc, s14, v6
	v_add_u32_e32 v8, 0x100, v10
	s_nop 0
	v_addc_co_u32_e32 v7, vcc, 0, v7, vcc
	global_load_ushort v13, v[6:7], off
	v_ashrrev_i16_e32 v6, 15, v4
	v_lshrrev_b16_e32 v6, 9, v6
	v_add_u16_e32 v18, v4, v6
	v_ashrrev_i16_e32 v6, 7, v18
	v_ashrrev_i32_e32 v8, 5, v8
	v_mul_hi_i32_i24_sdwa v7, sext(v6), s15 dst_sel:DWORD dst_unused:UNUSED_PAD src0_sel:WORD_0 src1_sel:DWORD
	v_mul_i32_i24_sdwa v6, sext(v6), s15 dst_sel:DWORD dst_unused:UNUSED_PAD src0_sel:WORD_0 src1_sel:DWORD
	v_ashrrev_i32_e32 v9, 31, v8
	v_lshl_add_u64 v[6:7], s[6:7], 0, v[6:7]
	v_lshlrev_b64 v[8:9], 13, v[8:9]
	v_lshl_add_u64 v[6:7], v[6:7], 0, v[8:9]
	v_and_b32_e32 v8, 0xffffff80, v18
	v_sub_u16_e32 v4, v4, v8
	v_lshlrev_b32_sdwa v8, v229, sext(v4) dst_sel:DWORD dst_unused:UNUSED_PAD src0_sel:DWORD src1_sel:WORD_0
	v_ashrrev_i32_e32 v9, 31, v8
	v_lshl_add_u64 v[6:7], v[8:9], 1, v[6:7]
	v_lshl_add_u64 v[6:7], v[6:7], 0, v[2:3]
	v_and_b32_e32 v2, 8, v10
	v_cmp_lt_i32_e32 vcc, s41, v1
	v_lshl_add_u64 v[6:7], v[6:7], 0, v[2:3]
	s_waitcnt vmcnt(0)
	v_perm_b32 v8, v11, v5, s23
	s_or_b64 s[10:11], vcc, s[10:11]
	v_perm_b32 v9, v15, v14, s23
	global_store_dwordx2 v[6:7], v[8:9], off
	v_perm_b32 v4, v17, v16, s23
	v_perm_b32 v5, v13, v12, s23
	global_store_dwordx2 v[6:7], v[4:5], off offset:16
	s_andn2_b64 exec, exec, s[10:11]
	s_cbranch_execnz .LBB0_747

.LBB0_764:
	v_lshrrev_b32_e32 v4, 9, v1
	v_bfe_u32 v2, v1, 3, 3
	v_lshrrev_b32_e32 v5, 4, v4
	v_lshl_or_b32 v2, v5, 3, v2
	v_and_b32_e32 v8, 15, v4
	v_bfe_u32 v5, v1, 6, 3
	v_lshl_or_b32 v8, v8, 3, v5
	v_and_b32_e32 v5, 7, v1
	v_lshl_or_b32 v8, v8, 3, v5
	v_lshlrev_b32_e32 v12, 3, v2
	v_ashrrev_i32_e32 v9, 31, v8
	v_mov_b64_e32 v[4:5], s[34:35]
	v_mad_i64_i32 v[6:7], s[6:7], v12, s27, v[4:5]
	v_lshlrev_b64 v[10:11], 1, v[8:9]
	v_lshl_add_u64 v[6:7], v[6:7], 0, v[10:11]
	global_load_ushort v13, v[6:7], off offset:2048
	v_or_b32_e32 v6, 1, v12
	v_mad_i64_i32 v[6:7], s[6:7], v6, s27, v[4:5]
	v_lshl_add_u64 v[6:7], v[6:7], 0, v[10:11]
	global_load_ushort v14, v[6:7], off offset:2048
	v_or_b32_e32 v6, 2, v12
	v_mad_i64_i32 v[6:7], s[6:7], v6, s27, v[4:5]
	v_lshl_add_u64 v[6:7], v[6:7], 0, v[10:11]
	global_load_ushort v15, v[6:7], off offset:2048
	v_or_b32_e32 v6, 3, v12
	v_mad_i64_i32 v[6:7], s[6:7], v6, s27, v[4:5]
	v_lshl_add_u64 v[6:7], v[6:7], 0, v[10:11]
	global_load_ushort v16, v[6:7], off offset:2048
	v_or_b32_e32 v6, 4, v12
	v_mad_i64_i32 v[6:7], s[6:7], v6, s27, v[4:5]
	v_lshl_add_u64 v[6:7], v[6:7], 0, v[10:11]
	global_load_ushort v17, v[6:7], off offset:2048
	v_or_b32_e32 v6, 5, v12
	v_mad_i64_i32 v[6:7], s[6:7], v6, s27, v[4:5]
	v_lshl_add_u64 v[6:7], v[6:7], 0, v[10:11]
	global_load_ushort v18, v[6:7], off offset:2048
	v_or_b32_e32 v6, 6, v12
	v_mad_i64_i32 v[6:7], s[6:7], v6, s27, v[4:5]
	v_lshl_add_u64 v[6:7], v[6:7], 0, v[10:11]
	global_load_ushort v6, v[6:7], off offset:2048
	v_or_b32_e32 v7, 7, v12
	v_mad_i64_i32 v[4:5], s[6:7], v7, s27, v[4:5]
	v_lshl_add_u64 v[4:5], v[4:5], 0, v[10:11]
	global_load_ushort v4, v[4:5], off offset:2048
	v_lshlrev_b64 v[8:9], 14, v[8:9]
	v_and_b32_e32 v10, -16, v12
	v_lshl_add_u64 v[8:9], s[52:53], 0, v[8:9]
	v_ashrrev_i32_e32 v11, 31, v10
	v_lshlrev_b32_e32 v2, 4, v2
	v_add_u32_e32 v1, s2, v1
	v_lshl_add_u64 v[8:9], v[10:11], 1, v[8:9]
	v_and_b32_e32 v2, 16, v2
	v_cmp_lt_i32_e32 vcc, s44, v1
	v_lshl_add_u64 v[8:9], v[8:9], 0, v[2:3]
	s_or_b64 s[4:5], vcc, s[4:5]
	s_waitcnt vmcnt(0)
	v_perm_b32 v5, v16, v15, s23
	v_perm_b32 v7, v4, v6, s23
	v_perm_b32 v6, v18, v17, s23
	v_perm_b32 v4, v14, v13, s23
	global_store_dwordx4 v[8:9], v[4:7], off
	s_andn2_b64 exec, exec, s[4:5]
	s_cbranch_execnz .LBB0_764

.LBB0_767:
	s_andn2_b64 vcc, exec, s[0:1]
	s_cbranch_vccnz .LBB0_786
	s_mov_b32 s0, s87
	v_mov_b32_e32 v2, v0
	s_mov_b32 s1, 0x200000
	v_lshl_add_u32 v1, s0, 9, v2
	v_cmp_gt_i32_e32 vcc, s1, v1
	s_and_saveexec_b64 s[6:7], vcc
	s_mov_b32 s14, 0xffff
	s_mov_b32 s12, 0x7ffff
	s_mov_b32 s13, 0x100000
	s_mov_b32 s15, 0xfffff
	s_movk_i32 s16, 0xf0
	s_mov_b32 s17, 0x504010c
	s_mov_b32 s18, 0x7060302
	s_cbranch_execz .LBB0_773
	v_and_b32_e32 v5, 64, v223
	v_xor_b32_e32 v4, 1, v223
	v_add_u32_e32 v5, 64, v5
	v_cmp_lt_i32_e32 vcc, v4, v5
	s_load_dwordx2 s[2:3], s[30:31], 0x170
	s_load_dword s1, s[20:21], 0x0
	v_cndmask_b32_e32 v4, v223, v4, vcc
	v_lshlrev_b32_e32 v12, 2, v4
	v_xor_b32_e32 v4, 2, v223
	v_cmp_lt_i32_e32 vcc, v4, v5
	s_waitcnt lgkmcnt(0)
	s_add_u32 s8, s2, 0x2000000
	v_lshlrev_b32_e32 v2, 3, v2
	v_cndmask_b32_e32 v4, v223, v4, vcc
	v_lshlrev_b32_e32 v13, 2, v4
	v_xor_b32_e32 v4, 4, v223
	v_cmp_lt_i32_e32 vcc, v4, v5
	s_addc_u32 s9, s3, 0
	s_lshl_b32 s2, s1, 9
	v_cndmask_b32_e32 v4, v223, v4, vcc
	v_lshlrev_b32_e32 v14, 2, v4
	v_lshl_add_u32 v15, s0, 12, v2
	s_lshl_b32 s3, s1, 12
	s_mov_b64 s[10:11], 0
	s_cmp_lg_u32 s2, 0x20000
	s_cbranch_scc1 .LBB0_771
	v_mov_b32_e32 v104, 0xa8
	global_load_dwordx4 v[100:103], v104, s[30:31]
	v_and_b32_e32 v106, 56, v15
	v_lshlrev_b32_e32 v106, 2, v106
	v_mov_b32_e32 v107, 0
	s_waitcnt vmcnt(0)
	v_lshl_add_u64 v[100:101], v[100:101], 0, v[106:107]
	v_lshl_add_u64 v[102:103], v[102:103], 0, v[106:107]
	global_load_dwordx4 v[80:83], v[100:101], off
	global_load_dwordx4 v[84:87], v[100:101], off offset:16
	global_load_dwordx4 v[88:91], v[102:103], off
	global_load_dwordx4 v[92:95], v[102:103], off offset:16
	s_waitcnt vmcnt(0)
.Lp0_loop:
	v_mov_b32_e32 v112, v1
	v_mov_b32_e32 v113, v15
	v_ashrrev_i32_e32 v2, 10, v1
	v_bfe_u32 v17, v1, 7, 13
	v_mov_b64_e32 v[4:5], s[34:35]
	v_and_b32_e32 v6, 0xfffffc00, v2
	v_bfe_u32 v16, v1, 3, 4
	v_mad_u64_u32 v[4:5], s[0:1], v17, s67, v[4:5]
	v_ashrrev_i32_e32 v7, 31, v6
	v_lshl_add_u64 v[4:5], v[6:7], 1, v[4:5]
	v_lshlrev_b32_e32 v2, 7, v16
	v_lshl_add_u64 v[4:5], v[4:5], 0, v[2:3]
	v_and_b32_e32 v2, 56, v15
	v_mov_b32_e32 v23, v3
	v_lshlrev_b32_e32 v22, 1, v2
	v_lshl_add_u64 v[4:5], v[4:5], 0, v[22:23]
	global_load_dwordx4 v[96:99], v[4:5], off
	v_add_u32_e32 v1, s2, v1
	v_add_u32_e32 v15, s3, v15
	v_ashrrev_i32_e32 v2, 10, v1
	v_bfe_u32 v17, v1, 7, 13
	v_mov_b64_e32 v[4:5], s[34:35]
	v_and_b32_e32 v6, 0xfffffc00, v2
	v_bfe_u32 v16, v1, 3, 4
	v_mad_u64_u32 v[4:5], s[0:1], v17, s67, v[4:5]
	v_ashrrev_i32_e32 v7, 31, v6
	v_lshl_add_u64 v[4:5], v[6:7], 1, v[4:5]
	v_lshlrev_b32_e32 v2, 7, v16
	v_lshl_add_u64 v[4:5], v[4:5], 0, v[2:3]
	v_and_b32_e32 v2, 56, v15
	v_mov_b32_e32 v23, v3
	v_lshlrev_b32_e32 v22, 1, v2
	v_lshl_add_u64 v[4:5], v[4:5], 0, v[22:23]
	global_load_dwordx4 v[100:103], v[4:5], off
	v_add_u32_e32 v1, s2, v1
	v_add_u32_e32 v15, s3, v15
	v_ashrrev_i32_e32 v2, 10, v1
	v_bfe_u32 v17, v1, 7, 13
	v_mov_b64_e32 v[4:5], s[34:35]
	v_and_b32_e32 v6, 0xfffffc00, v2
	v_bfe_u32 v16, v1, 3, 4
	v_mad_u64_u32 v[4:5], s[0:1], v17, s67, v[4:5]
	v_ashrrev_i32_e32 v7, 31, v6
	v_lshl_add_u64 v[4:5], v[6:7], 1, v[4:5]
	v_lshlrev_b32_e32 v2, 7, v16
	v_lshl_add_u64 v[4:5], v[4:5], 0, v[2:3]
	v_and_b32_e32 v2, 56, v15
	v_mov_b32_e32 v23, v3
	v_lshlrev_b32_e32 v22, 1, v2
	v_lshl_add_u64 v[4:5], v[4:5], 0, v[22:23]
	global_load_dwordx4 v[104:107], v[4:5], off
	v_add_u32_e32 v1, s2, v1
	v_add_u32_e32 v15, s3, v15
	v_ashrrev_i32_e32 v2, 10, v1
	v_bfe_u32 v17, v1, 7, 13
	v_mov_b64_e32 v[4:5], s[34:35]
	v_and_b32_e32 v6, 0xfffffc00, v2
	v_bfe_u32 v16, v1, 3, 4
	v_mad_u64_u32 v[4:5], s[0:1], v17, s67, v[4:5]
	v_ashrrev_i32_e32 v7, 31, v6
	v_lshl_add_u64 v[4:5], v[6:7], 1, v[4:5]
	v_lshlrev_b32_e32 v2, 7, v16
	v_lshl_add_u64 v[4:5], v[4:5], 0, v[2:3]
	v_and_b32_e32 v2, 56, v15
	v_mov_b32_e32 v23, v3
	v_lshlrev_b32_e32 v22, 1, v2
	v_lshl_add_u64 v[4:5], v[4:5], 0, v[22:23]
	global_load_dwordx4 v[108:111], v[4:5], off
	v_mov_b32_e32 v1, v112
	v_mov_b32_e32 v15, v113
	v_ashrrev_i32_e32 v2, 10, v1
	v_bfe_u32 v17, v1, 7, 13
	v_mov_b64_e32 v[4:5], s[34:35]
	v_and_b32_e32 v6, 0xfffffc00, v2
	v_bfe_u32 v16, v1, 3, 4
	v_mad_u64_u32 v[4:5], s[0:1], v17, s67, v[4:5]
	v_ashrrev_i32_e32 v7, 31, v6
	v_lshl_add_u64 v[4:5], v[6:7], 1, v[4:5]
	v_lshlrev_b32_e32 v2, 7, v16
	v_lshl_add_u64 v[4:5], v[4:5], 0, v[2:3]
	v_cmp_lt_u32_e32 vcc, s15, v1
	v_and_b32_e32 v2, 56, v15
	v_mov_b32_e32 v23, v3
	v_lshlrev_b32_e32 v22, 1, v2
	v_lshl_add_u64 v[4:5], v[4:5], 0, v[22:23]
	s_waitcnt vmcnt(3)
	v_mov_b64_e32 v[4:5], v[96:97]
	v_mov_b64_e32 v[6:7], v[98:99]
	v_lshlrev_b32_e32 v2, 2, v2
	v_mov_b32_e32 v37, 0xe8a0000
	s_movk_i32 s0, 0x1000
	v_cmp_gt_u32_e64 s[0:1], s0, v17
	v_cndmask_b32_e32 v8, v80, v88, vcc
	v_cndmask_b32_e32 v9, v81, v89, vcc
	v_cndmask_b32_e32 v10, v82, v90, vcc
	v_cndmask_b32_e32 v11, v83, v91, vcc
	v_cndmask_b32_e32 v18, v84, v92, vcc
	v_cndmask_b32_e32 v19, v85, v93, vcc
	v_cndmask_b32_e32 v20, v86, v94, vcc
	v_cndmask_b32_e32 v21, v87, v95, vcc
	v_lshlrev_b32_e32 v24, 16, v4
	v_and_b32_e32 v25, 0xffff0000, v4
	v_lshlrev_b32_e32 v4, 16, v5
	v_and_b32_e32 v5, 0xffff0000, v5
	v_pk_mul_f32 v[28:29], v[24:25], v[24:25]
	v_pk_mul_f32 v[30:31], v[4:5], v[4:5]
	v_add_f32_e32 v28, v28, v29
	v_lshlrev_b32_e32 v26, 16, v6
	v_and_b32_e32 v27, 0xffff0000, v6
	v_add_f32_e32 v28, v28, v30
	v_pk_mul_f32 v[32:33], v[26:27], v[26:27]
	v_add_f32_e32 v28, v31, v28
	v_lshlrev_b32_e32 v6, 16, v7
	v_and_b32_e32 v7, 0xffff0000, v7
	v_add_f32_e32 v28, v32, v28
	v_pk_mul_f32 v[34:35], v[6:7], v[6:7]
	v_add_f32_e32 v28, v33, v28
	v_add_f32_e32 v28, v34, v28
	v_add_f32_e32 v28, v35, v28
	ds_bpermute_b32 v30, v12, v28
	v_mov_b32_e32 v29, v3
	v_mov_b32_e32 v31, v3
	v_mov_b32_e32 v33, v3
	v_lshlrev_b32_e32 v32, 7, v17
	s_waitcnt lgkmcnt(0)
	v_add_f32_e32 v28, v28, v30
	ds_bpermute_b32 v34, v13, v28
	v_lshlrev_b32_e32 v30, 20, v16
	v_cndmask_b32_e64 v17, v232, 1.0, vcc
	s_waitcnt lgkmcnt(0)
	v_add_f32_e32 v34, v28, v34
	ds_bpermute_b32 v35, v14, v34
	v_mov_b32_e32 v28, 0xd8a0000
	v_cndmask_b32_e32 v28, v28, v37, vcc
	v_lshl_add_u64 v[28:29], s[28:29], 0, v[28:29]
	v_lshl_add_u64 v[28:29], v[28:29], 0, v[30:31]
	s_waitcnt lgkmcnt(0)
	v_add_f32_e32 v34, v34, v35
	v_fmamk_f32 v34, v34, 0x3c800000, v218
	v_mul_f32_e32 v35, 0x4b800000, v34
	v_cmp_gt_f32_e64 s[4:5], s71, v34
	v_lshl_add_u64 v[28:29], v[28:29], 0, v[32:33]
	v_lshl_add_u64 v[22:23], v[28:29], 0, v[22:23]
	v_cndmask_b32_e64 v34, v34, v35, s[4:5]
	v_rsq_f32_e32 v34, v34
	s_nop 0
	v_mul_f32_e32 v28, 0x45800000, v34
	v_cndmask_b32_e64 v28, v34, v28, s[4:5]
	v_mul_f32_e32 v28, v17, v28
	s_and_b64 s[4:5], vcc, s[0:1]
	v_pk_mul_f32 v[8:9], v[8:9], v[28:29] op_sel_hi:[1,0]
	v_pk_mul_f32 v[10:11], v[10:11], v[28:29] op_sel_hi:[1,0]
	v_pk_mul_f32 v[18:19], v[18:19], v[28:29] op_sel_hi:[1,0]
	v_pk_mul_f32 v[20:21], v[20:21], v[28:29] op_sel_hi:[1,0]
	v_pk_mul_f32 v[8:9], v[8:9], v[24:25]
	v_pk_mul_f32 v[10:11], v[10:11], v[4:5]
	v_pk_mul_f32 v[4:5], v[18:19], v[26:27]
	v_pk_mul_f32 v[6:7], v[20:21], v[6:7]
	v_cvt_pk_bf16_f32 v18, v8, v9
	v_cvt_pk_bf16_f32 v19, v10, v11
	v_cvt_pk_bf16_f32 v20, v4, v5
	v_cvt_pk_bf16_f32 v21, v6, v7
	global_store_dwordx4 v[22:23], v[18:21], off
	s_and_saveexec_b64 s[0:1], s[4:5]
	s_cbranch_execz .Lp0_t0
	v_lshrrev_b32_e32 v17, 7, v1
	v_lshrrev_b32_e32 v18, 11, v1
	v_and_or_b32 v16, v18, s16, v16
	v_lshlrev_b32_e32 v17, 8, v17
	v_perm_b32 v16, v16, v17, s17
	v_mov_b32_e32 v17, v3
	v_lshl_add_u64 v[16:17], s[8:9], 0, v[16:17]
	v_lshl_add_u64 v[16:17], v[16:17], 0, v[2:3]
	global_store_dwordx4 v[16:17], v[8:11], off
	global_store_dwordx4 v[16:17], v[4:7], off offset:16
.Lp0_t0:
	s_or_b64 exec, exec, s[0:1]
	v_add_u32_e32 v1, s2, v1
	v_add_u32_e32 v15, s3, v15
	v_ashrrev_i32_e32 v2, 10, v1
	v_bfe_u32 v17, v1, 7, 13
	v_mov_b64_e32 v[4:5], s[34:35]
	v_and_b32_e32 v6, 0xfffffc00, v2
	v_bfe_u32 v16, v1, 3, 4
	v_mad_u64_u32 v[4:5], s[0:1], v17, s67, v[4:5]
	v_ashrrev_i32_e32 v7, 31, v6
	v_lshl_add_u64 v[4:5], v[6:7], 1, v[4:5]
	v_lshlrev_b32_e32 v2, 7, v16
	v_lshl_add_u64 v[4:5], v[4:5], 0, v[2:3]
	v_cmp_lt_u32_e32 vcc, s15, v1
	v_and_b32_e32 v2, 56, v15
	v_mov_b32_e32 v23, v3
	v_lshlrev_b32_e32 v22, 1, v2
	v_lshl_add_u64 v[4:5], v[4:5], 0, v[22:23]
	s_waitcnt vmcnt(3)
	v_mov_b64_e32 v[4:5], v[100:101]
	v_mov_b64_e32 v[6:7], v[102:103]
	v_lshlrev_b32_e32 v2, 2, v2
	v_mov_b32_e32 v37, 0xe8a0000
	s_movk_i32 s0, 0x1000
	v_cmp_gt_u32_e64 s[0:1], s0, v17
	v_cndmask_b32_e32 v8, v80, v88, vcc
	v_cndmask_b32_e32 v9, v81, v89, vcc
	v_cndmask_b32_e32 v10, v82, v90, vcc
	v_cndmask_b32_e32 v11, v83, v91, vcc
	v_cndmask_b32_e32 v18, v84, v92, vcc
	v_cndmask_b32_e32 v19, v85, v93, vcc
	v_cndmask_b32_e32 v20, v86, v94, vcc
	v_cndmask_b32_e32 v21, v87, v95, vcc
	v_lshlrev_b32_e32 v24, 16, v4
	v_and_b32_e32 v25, 0xffff0000, v4
	v_lshlrev_b32_e32 v4, 16, v5
	v_and_b32_e32 v5, 0xffff0000, v5
	v_pk_mul_f32 v[28:29], v[24:25], v[24:25]
	v_pk_mul_f32 v[30:31], v[4:5], v[4:5]
	v_add_f32_e32 v28, v28, v29
	v_lshlrev_b32_e32 v26, 16, v6
	v_and_b32_e32 v27, 0xffff0000, v6
	v_add_f32_e32 v28, v28, v30
	v_pk_mul_f32 v[32:33], v[26:27], v[26:27]
	v_add_f32_e32 v28, v31, v28
	v_lshlrev_b32_e32 v6, 16, v7
	v_and_b32_e32 v7, 0xffff0000, v7
	v_add_f32_e32 v28, v32, v28
	v_pk_mul_f32 v[34:35], v[6:7], v[6:7]
	v_add_f32_e32 v28, v33, v28
	v_add_f32_e32 v28, v34, v28
	v_add_f32_e32 v28, v35, v28
	ds_bpermute_b32 v30, v12, v28
	v_mov_b32_e32 v29, v3
	v_mov_b32_e32 v31, v3
	v_mov_b32_e32 v33, v3
	v_lshlrev_b32_e32 v32, 7, v17
	s_waitcnt lgkmcnt(0)
	v_add_f32_e32 v28, v28, v30
	ds_bpermute_b32 v34, v13, v28
	v_lshlrev_b32_e32 v30, 20, v16
	v_cndmask_b32_e64 v17, v232, 1.0, vcc
	s_waitcnt lgkmcnt(0)
	v_add_f32_e32 v34, v28, v34
	ds_bpermute_b32 v35, v14, v34
	v_mov_b32_e32 v28, 0xd8a0000
	v_cndmask_b32_e32 v28, v28, v37, vcc
	v_lshl_add_u64 v[28:29], s[28:29], 0, v[28:29]
	v_lshl_add_u64 v[28:29], v[28:29], 0, v[30:31]
	s_waitcnt lgkmcnt(0)
	v_add_f32_e32 v34, v34, v35
	v_fmamk_f32 v34, v34, 0x3c800000, v218
	v_mul_f32_e32 v35, 0x4b800000, v34
	v_cmp_gt_f32_e64 s[4:5], s71, v34
	v_lshl_add_u64 v[28:29], v[28:29], 0, v[32:33]
	v_lshl_add_u64 v[22:23], v[28:29], 0, v[22:23]
	v_cndmask_b32_e64 v34, v34, v35, s[4:5]
	v_rsq_f32_e32 v34, v34
	s_nop 0
	v_mul_f32_e32 v28, 0x45800000, v34
	v_cndmask_b32_e64 v28, v34, v28, s[4:5]
	v_mul_f32_e32 v28, v17, v28
	s_and_b64 s[4:5], vcc, s[0:1]
	v_pk_mul_f32 v[8:9], v[8:9], v[28:29] op_sel_hi:[1,0]
	v_pk_mul_f32 v[10:11], v[10:11], v[28:29] op_sel_hi:[1,0]
	v_pk_mul_f32 v[18:19], v[18:19], v[28:29] op_sel_hi:[1,0]
	v_pk_mul_f32 v[20:21], v[20:21], v[28:29] op_sel_hi:[1,0]
	v_pk_mul_f32 v[8:9], v[8:9], v[24:25]
	v_pk_mul_f32 v[10:11], v[10:11], v[4:5]
	v_pk_mul_f32 v[4:5], v[18:19], v[26:27]
	v_pk_mul_f32 v[6:7], v[20:21], v[6:7]
	v_cvt_pk_bf16_f32 v18, v8, v9
	v_cvt_pk_bf16_f32 v19, v10, v11
	v_cvt_pk_bf16_f32 v20, v4, v5
	v_cvt_pk_bf16_f32 v21, v6, v7
	global_store_dwordx4 v[22:23], v[18:21], off
	s_and_saveexec_b64 s[0:1], s[4:5]
	s_cbranch_execz .Lp0_t1
	v_lshrrev_b32_e32 v17, 7, v1
	v_lshrrev_b32_e32 v18, 11, v1
	v_and_or_b32 v16, v18, s16, v16
	v_lshlrev_b32_e32 v17, 8, v17
	v_perm_b32 v16, v16, v17, s17
	v_mov_b32_e32 v17, v3
	v_lshl_add_u64 v[16:17], s[8:9], 0, v[16:17]
	v_lshl_add_u64 v[16:17], v[16:17], 0, v[2:3]
	global_store_dwordx4 v[16:17], v[8:11], off
	global_store_dwordx4 v[16:17], v[4:7], off offset:16
.Lp0_t1:
	s_or_b64 exec, exec, s[0:1]
	v_add_u32_e32 v1, s2, v1
	v_add_u32_e32 v15, s3, v15
	v_ashrrev_i32_e32 v2, 10, v1
	v_bfe_u32 v17, v1, 7, 13
	v_mov_b64_e32 v[4:5], s[34:35]
	v_and_b32_e32 v6, 0xfffffc00, v2
	v_bfe_u32 v16, v1, 3, 4
	v_mad_u64_u32 v[4:5], s[0:1], v17, s67, v[4:5]
	v_ashrrev_i32_e32 v7, 31, v6
	v_lshl_add_u64 v[4:5], v[6:7], 1, v[4:5]
	v_lshlrev_b32_e32 v2, 7, v16
	v_lshl_add_u64 v[4:5], v[4:5], 0, v[2:3]
	v_cmp_lt_u32_e32 vcc, s15, v1
	v_and_b32_e32 v2, 56, v15
	v_mov_b32_e32 v23, v3
	v_lshlrev_b32_e32 v22, 1, v2
	v_lshl_add_u64 v[4:5], v[4:5], 0, v[22:23]
	s_waitcnt vmcnt(3)
	v_mov_b64_e32 v[4:5], v[104:105]
	v_mov_b64_e32 v[6:7], v[106:107]
	v_lshlrev_b32_e32 v2, 2, v2
	v_mov_b32_e32 v37, 0xe8a0000
	s_movk_i32 s0, 0x1000
	v_cmp_gt_u32_e64 s[0:1], s0, v17
	v_cndmask_b32_e32 v8, v80, v88, vcc
	v_cndmask_b32_e32 v9, v81, v89, vcc
	v_cndmask_b32_e32 v10, v82, v90, vcc
	v_cndmask_b32_e32 v11, v83, v91, vcc
	v_cndmask_b32_e32 v18, v84, v92, vcc
	v_cndmask_b32_e32 v19, v85, v93, vcc
	v_cndmask_b32_e32 v20, v86, v94, vcc
	v_cndmask_b32_e32 v21, v87, v95, vcc
	v_lshlrev_b32_e32 v24, 16, v4
	v_and_b32_e32 v25, 0xffff0000, v4
	v_lshlrev_b32_e32 v4, 16, v5
	v_and_b32_e32 v5, 0xffff0000, v5
	v_pk_mul_f32 v[28:29], v[24:25], v[24:25]
	v_pk_mul_f32 v[30:31], v[4:5], v[4:5]
	v_add_f32_e32 v28, v28, v29
	v_lshlrev_b32_e32 v26, 16, v6
	v_and_b32_e32 v27, 0xffff0000, v6
	v_add_f32_e32 v28, v28, v30
	v_pk_mul_f32 v[32:33], v[26:27], v[26:27]
	v_add_f32_e32 v28, v31, v28
	v_lshlrev_b32_e32 v6, 16, v7
	v_and_b32_e32 v7, 0xffff0000, v7
	v_add_f32_e32 v28, v32, v28
	v_pk_mul_f32 v[34:35], v[6:7], v[6:7]
	v_add_f32_e32 v28, v33, v28
	v_add_f32_e32 v28, v34, v28
	v_add_f32_e32 v28, v35, v28
	ds_bpermute_b32 v30, v12, v28
	v_mov_b32_e32 v29, v3
	v_mov_b32_e32 v31, v3
	v_mov_b32_e32 v33, v3
	v_lshlrev_b32_e32 v32, 7, v17
	s_waitcnt lgkmcnt(0)
	v_add_f32_e32 v28, v28, v30
	ds_bpermute_b32 v34, v13, v28
	v_lshlrev_b32_e32 v30, 20, v16
	v_cndmask_b32_e64 v17, v232, 1.0, vcc
	s_waitcnt lgkmcnt(0)
	v_add_f32_e32 v34, v28, v34
	ds_bpermute_b32 v35, v14, v34
	v_mov_b32_e32 v28, 0xd8a0000
	v_cndmask_b32_e32 v28, v28, v37, vcc
	v_lshl_add_u64 v[28:29], s[28:29], 0, v[28:29]
	v_lshl_add_u64 v[28:29], v[28:29], 0, v[30:31]
	s_waitcnt lgkmcnt(0)
	v_add_f32_e32 v34, v34, v35
	v_fmamk_f32 v34, v34, 0x3c800000, v218
	v_mul_f32_e32 v35, 0x4b800000, v34
	v_cmp_gt_f32_e64 s[4:5], s71, v34
	v_lshl_add_u64 v[28:29], v[28:29], 0, v[32:33]
	v_lshl_add_u64 v[22:23], v[28:29], 0, v[22:23]
	v_cndmask_b32_e64 v34, v34, v35, s[4:5]
	v_rsq_f32_e32 v34, v34
	s_nop 0
	v_mul_f32_e32 v28, 0x45800000, v34
	v_cndmask_b32_e64 v28, v34, v28, s[4:5]
	v_mul_f32_e32 v28, v17, v28
	s_and_b64 s[4:5], vcc, s[0:1]
	v_pk_mul_f32 v[8:9], v[8:9], v[28:29] op_sel_hi:[1,0]
	v_pk_mul_f32 v[10:11], v[10:11], v[28:29] op_sel_hi:[1,0]
	v_pk_mul_f32 v[18:19], v[18:19], v[28:29] op_sel_hi:[1,0]
	v_pk_mul_f32 v[20:21], v[20:21], v[28:29] op_sel_hi:[1,0]
	v_pk_mul_f32 v[8:9], v[8:9], v[24:25]
	v_pk_mul_f32 v[10:11], v[10:11], v[4:5]
	v_pk_mul_f32 v[4:5], v[18:19], v[26:27]
	v_pk_mul_f32 v[6:7], v[20:21], v[6:7]
	v_cvt_pk_bf16_f32 v18, v8, v9
	v_cvt_pk_bf16_f32 v19, v10, v11
	v_cvt_pk_bf16_f32 v20, v4, v5
	v_cvt_pk_bf16_f32 v21, v6, v7
	global_store_dwordx4 v[22:23], v[18:21], off
	s_and_saveexec_b64 s[0:1], s[4:5]
	s_cbranch_execz .Lp0_t2
	v_lshrrev_b32_e32 v17, 7, v1
	v_lshrrev_b32_e32 v18, 11, v1
	v_and_or_b32 v16, v18, s16, v16
	v_lshlrev_b32_e32 v17, 8, v17
	v_perm_b32 v16, v16, v17, s17
	v_mov_b32_e32 v17, v3
	v_lshl_add_u64 v[16:17], s[8:9], 0, v[16:17]
	v_lshl_add_u64 v[16:17], v[16:17], 0, v[2:3]
	global_store_dwordx4 v[16:17], v[8:11], off
	global_store_dwordx4 v[16:17], v[4:7], off offset:16
.Lp0_t2:
	s_or_b64 exec, exec, s[0:1]
	v_add_u32_e32 v1, s2, v1
	v_add_u32_e32 v15, s3, v15
	v_ashrrev_i32_e32 v2, 10, v1
	v_bfe_u32 v17, v1, 7, 13
	v_mov_b64_e32 v[4:5], s[34:35]
	v_and_b32_e32 v6, 0xfffffc00, v2
	v_bfe_u32 v16, v1, 3, 4
	v_mad_u64_u32 v[4:5], s[0:1], v17, s67, v[4:5]
	v_ashrrev_i32_e32 v7, 31, v6
	v_lshl_add_u64 v[4:5], v[6:7], 1, v[4:5]
	v_lshlrev_b32_e32 v2, 7, v16
	v_lshl_add_u64 v[4:5], v[4:5], 0, v[2:3]
	v_cmp_lt_u32_e32 vcc, s15, v1
	v_and_b32_e32 v2, 56, v15
	v_mov_b32_e32 v23, v3
	v_lshlrev_b32_e32 v22, 1, v2
	v_lshl_add_u64 v[4:5], v[4:5], 0, v[22:23]
	s_waitcnt vmcnt(3)
	v_mov_b64_e32 v[4:5], v[108:109]
	v_mov_b64_e32 v[6:7], v[110:111]
	v_lshlrev_b32_e32 v2, 2, v2
	v_mov_b32_e32 v37, 0xe8a0000
	s_movk_i32 s0, 0x1000
	v_cmp_gt_u32_e64 s[0:1], s0, v17
	v_cndmask_b32_e32 v8, v80, v88, vcc
	v_cndmask_b32_e32 v9, v81, v89, vcc
	v_cndmask_b32_e32 v10, v82, v90, vcc
	v_cndmask_b32_e32 v11, v83, v91, vcc
	v_cndmask_b32_e32 v18, v84, v92, vcc
	v_cndmask_b32_e32 v19, v85, v93, vcc
	v_cndmask_b32_e32 v20, v86, v94, vcc
	v_cndmask_b32_e32 v21, v87, v95, vcc
	v_lshlrev_b32_e32 v24, 16, v4
	v_and_b32_e32 v25, 0xffff0000, v4
	v_lshlrev_b32_e32 v4, 16, v5
	v_and_b32_e32 v5, 0xffff0000, v5
	v_pk_mul_f32 v[28:29], v[24:25], v[24:25]
	v_pk_mul_f32 v[30:31], v[4:5], v[4:5]
	v_add_f32_e32 v28, v28, v29
	v_lshlrev_b32_e32 v26, 16, v6
	v_and_b32_e32 v27, 0xffff0000, v6
	v_add_f32_e32 v28, v28, v30
	v_pk_mul_f32 v[32:33], v[26:27], v[26:27]
	v_add_f32_e32 v28, v31, v28
	v_lshlrev_b32_e32 v6, 16, v7
	v_and_b32_e32 v7, 0xffff0000, v7
	v_add_f32_e32 v28, v32, v28
	v_pk_mul_f32 v[34:35], v[6:7], v[6:7]
	v_add_f32_e32 v28, v33, v28
	v_add_f32_e32 v28, v34, v28
	v_add_f32_e32 v28, v35, v28
	ds_bpermute_b32 v30, v12, v28
	v_mov_b32_e32 v29, v3
	v_mov_b32_e32 v31, v3
	v_mov_b32_e32 v33, v3
	v_lshlrev_b32_e32 v32, 7, v17
	s_waitcnt lgkmcnt(0)
	v_add_f32_e32 v28, v28, v30
	ds_bpermute_b32 v34, v13, v28
	v_lshlrev_b32_e32 v30, 20, v16
	v_cndmask_b32_e64 v17, v232, 1.0, vcc
	s_waitcnt lgkmcnt(0)
	v_add_f32_e32 v34, v28, v34
	ds_bpermute_b32 v35, v14, v34
	v_mov_b32_e32 v28, 0xd8a0000
	v_cndmask_b32_e32 v28, v28, v37, vcc
	v_lshl_add_u64 v[28:29], s[28:29], 0, v[28:29]
	v_lshl_add_u64 v[28:29], v[28:29], 0, v[30:31]
	s_waitcnt lgkmcnt(0)
	v_add_f32_e32 v34, v34, v35
	v_fmamk_f32 v34, v34, 0x3c800000, v218
	v_mul_f32_e32 v35, 0x4b800000, v34
	v_cmp_gt_f32_e64 s[4:5], s71, v34
	v_lshl_add_u64 v[28:29], v[28:29], 0, v[32:33]
	v_lshl_add_u64 v[22:23], v[28:29], 0, v[22:23]
	v_cndmask_b32_e64 v34, v34, v35, s[4:5]
	v_rsq_f32_e32 v34, v34
	s_nop 0
	v_mul_f32_e32 v28, 0x45800000, v34
	v_cndmask_b32_e64 v28, v34, v28, s[4:5]
	v_mul_f32_e32 v28, v17, v28
	s_and_b64 s[4:5], vcc, s[0:1]
	v_pk_mul_f32 v[8:9], v[8:9], v[28:29] op_sel_hi:[1,0]
	v_pk_mul_f32 v[10:11], v[10:11], v[28:29] op_sel_hi:[1,0]
	v_pk_mul_f32 v[18:19], v[18:19], v[28:29] op_sel_hi:[1,0]
	v_pk_mul_f32 v[20:21], v[20:21], v[28:29] op_sel_hi:[1,0]
	v_pk_mul_f32 v[8:9], v[8:9], v[24:25]
	v_pk_mul_f32 v[10:11], v[10:11], v[4:5]
	v_pk_mul_f32 v[4:5], v[18:19], v[26:27]
	v_pk_mul_f32 v[6:7], v[20:21], v[6:7]
	v_cvt_pk_bf16_f32 v18, v8, v9
	v_cvt_pk_bf16_f32 v19, v10, v11
	v_cvt_pk_bf16_f32 v20, v4, v5
	v_cvt_pk_bf16_f32 v21, v6, v7
	global_store_dwordx4 v[22:23], v[18:21], off
	s_and_saveexec_b64 s[0:1], s[4:5]
	s_cbranch_execz .Lp0_t3
	v_lshrrev_b32_e32 v17, 7, v1
	v_lshrrev_b32_e32 v18, 11, v1
	v_and_or_b32 v16, v18, s16, v16
	v_lshlrev_b32_e32 v17, 8, v17
	v_perm_b32 v16, v16, v17, s17
	v_mov_b32_e32 v17, v3
	v_lshl_add_u64 v[16:17], s[8:9], 0, v[16:17]
	v_lshl_add_u64 v[16:17], v[16:17], 0, v[2:3]
	global_store_dwordx4 v[16:17], v[8:11], off
	global_store_dwordx4 v[16:17], v[4:7], off offset:16
.Lp0_t3:
	s_or_b64 exec, exec, s[0:1]
	v_add_u32_e32 v1, s2, v1
	v_add_u32_e32 v15, s3, v15
	v_cmp_lt_i32_e32 vcc, s33, v1
	s_or_b64 s[10:11], vcc, s[10:11]
	s_andn2_b64 exec, exec, s[10:11]
	s_cbranch_execz .LBB0_773
	s_branch .Lp0_loop

.LBB0_778:
	v_lshrrev_b32_e32 v120, 9, v1
	v_bfe_u32 v121, v1, 3, 3
	v_lshrrev_b32_e32 v122, 4, v120
	v_lshl_or_b32 v122, v122, 3, v121
	v_and_b32_e32 v120, 15, v120
	v_bfe_u32 v121, v1, 6, 3
	v_lshl_or_b32 v120, v120, 3, v121
	v_and_b32_e32 v121, 7, v1
	v_lshl_or_b32 v120, v120, 3, v121
	v_mov_b32_e32 v2, v122
	v_mov_b32_e32 v4, v120
	v_lshlrev_b32_e32 v2, 3, v2
	v_ashrrev_i32_e32 v5, 31, v4
	v_mov_b64_e32 v[8:9], s[34:35]
	v_mad_i64_i32 v[10:11], s[6:7], v2, s67, v[8:9]
	v_lshlrev_b64 v[6:7], 1, v[4:5]
	v_lshl_add_u64 v[10:11], v[10:11], 0, v[6:7]
	v_add_co_u32_e32 v10, vcc, 0x1000, v10
	v_lshlrev_b64 v[4:5], 14, v[4:5]
	s_nop 0
	v_addc_co_u32_e32 v11, vcc, 0, v11, vcc
	global_load_ushort v12, v[10:11], off
	v_or_b32_e32 v10, 1, v2
	v_mad_i64_i32 v[10:11], s[6:7], v10, s67, v[8:9]
	v_lshl_add_u64 v[10:11], v[10:11], 0, v[6:7]
	v_add_co_u32_e32 v10, vcc, 0x1000, v10
	v_lshl_add_u64 v[4:5], s[54:55], 0, v[4:5]
	s_nop 0
	v_addc_co_u32_e32 v11, vcc, 0, v11, vcc
	global_load_ushort v13, v[10:11], off
	v_or_b32_e32 v10, 2, v2
	v_mad_i64_i32 v[10:11], s[6:7], v10, s67, v[8:9]
	v_lshl_add_u64 v[10:11], v[10:11], 0, v[6:7]
	v_add_co_u32_e32 v10, vcc, 0x1000, v10
	v_add_u32_e32 v1, s2, v1
	s_nop 0
	v_addc_co_u32_e32 v11, vcc, 0, v11, vcc
	global_load_ushort v14, v[10:11], off
	v_or_b32_e32 v10, 3, v2
	v_mad_i64_i32 v[10:11], s[6:7], v10, s67, v[8:9]
	v_lshl_add_u64 v[10:11], v[10:11], 0, v[6:7]
	v_add_co_u32_e32 v10, vcc, 0x1000, v10
	s_nop 1
	v_addc_co_u32_e32 v11, vcc, 0, v11, vcc
	global_load_ushort v15, v[10:11], off
	v_or_b32_e32 v10, 4, v2
	v_mad_i64_i32 v[10:11], s[6:7], v10, s67, v[8:9]
	v_lshl_add_u64 v[10:11], v[10:11], 0, v[6:7]
	v_add_co_u32_e32 v10, vcc, 0x1000, v10
	s_nop 1
	v_addc_co_u32_e32 v11, vcc, 0, v11, vcc
	global_load_ushort v16, v[10:11], off
	v_or_b32_e32 v10, 5, v2
	v_mad_i64_i32 v[10:11], s[6:7], v10, s67, v[8:9]
	v_lshl_add_u64 v[10:11], v[10:11], 0, v[6:7]
	v_add_co_u32_e32 v10, vcc, 0x1000, v10
	s_nop 1
	v_addc_co_u32_e32 v11, vcc, 0, v11, vcc
	global_load_ushort v17, v[10:11], off
	v_or_b32_e32 v10, 6, v2
	v_mad_i64_i32 v[10:11], s[6:7], v10, s67, v[8:9]
	v_lshl_add_u64 v[10:11], v[10:11], 0, v[6:7]
	v_add_co_u32_e32 v10, vcc, 0x1000, v10
	s_nop 1
	v_addc_co_u32_e32 v11, vcc, 0, v11, vcc
	global_load_ushort v10, v[10:11], off
	v_or_b32_e32 v11, 7, v2
	v_mad_i64_i32 v[8:9], s[6:7], v11, s67, v[8:9]
	v_lshl_add_u64 v[6:7], v[8:9], 0, v[6:7]
	v_add_co_u32_e32 v6, vcc, 0x1000, v6
	s_nop 1
	v_addc_co_u32_e32 v7, vcc, 0, v7, vcc
	global_load_ushort v8, v[6:7], off
	v_and_b32_e32 v6, -16, v2
	v_ashrrev_i32_e32 v7, 31, v6
	v_lshl_add_u64 v[4:5], v[6:7], 1, v[4:5]
	v_and_b32_e32 v2, 8, v2
	v_lshl_add_u64 v[4:5], v[4:5], 0, v[2:3]
	v_cmp_lt_i32_e32 vcc, s15, v1
	s_or_b64 s[4:5], vcc, s[4:5]
	s_waitcnt vmcnt(0)
	v_perm_b32 v6, v13, v12, s23
	v_perm_b32 v7, v15, v14, s23
	global_store_dwordx2 v[4:5], v[6:7], off
	v_perm_b32 v6, v17, v16, s23
	v_perm_b32 v7, v8, v10, s23
	global_store_dwordx2 v[4:5], v[6:7], off offset:16
	s_andn2_b64 exec, exec, s[4:5]
	s_cbranch_execnz .LBB0_778
